# scan consumer chain: the four state-update MFMAs of each chunk issued ahead of the DPP statistics block (critical path to the next chunk), lgkmcnt re-derived; on top of consumer-wave priority
# baseline (speedup 1.0000x reference)
; __device__ __forceinline__ void ck_consume(const LAS unsigned char* slot, f32x4 (&sacc)[4], LAS unsigned char* st  , int lane, int cw, f32x4& yout, u32x2& vout, f32x4& dout) {
;     ...
;     for (int ks = 0; ks < 2; ++ks)
; #pragma unroll
;         for (int mt = 0; mt < 2; ++mt) { const LAS unsigned char* p = slot + CK_QR + (16 * mt + n) * 136 + (32 * ks + 4 * g) * 2; qlo[ks][mt] = ck_ld8(p); qhi[ks][mt] = ck_ld8(p + 32); }
;     const u32x2 vq = ck_ld8(slot + CK_VT + (16 * cw + n) * 40 + 8 * g);
;     const u32x2 mk = ck_ld8(slot + CK_MK + n * 40 + 8 * g);
; #pragma unroll
;     for (int j = 0; j < 4; ++j) mn[j] = ck_ld8(slot + CK_MN + j * 640 + n * 40 + 8 * g);
;     const u32x2 ylo = ck_ld8(slot + CK_MY + n * 72 + 8 * g), yhi = ck_ld8(slot + CK_MY + n * 72 + 8 * g + 32);
; #pragma unroll
;     for (int kb = 0; kb < 4; ++kb) { const LAS unsigned char* p = slot + CK_BK + (16 * kb + n) * 72 + 8 * g; blo[kb] = ck_ld8(p); bhi[kb] = ck_ld8(p + 32); gm[kb] = *(const LAS f32x4*)(slot + CK_GM + (16 * kb + 4 * g) * 4); }
;     f32x4 xacc[2] = {zero4, zero4};
; #pragma unroll
;     for (int ks = 0; ks < 2; ++ks) {
;         const pg8::bf16x8 Bs = ck_frag(pkc(sacc[2 * ks][0], sacc[2 * ks][1]), pkc(sacc[2 * ks][2], sacc[2 * ks][3]), pkc(sacc[2 * ks + 1][0], sacc[2 * ks + 1][1]), pkc(sacc[2 * ks + 1][2], sacc[2 * ks + 1][3]));
; #pragma unroll
;         for (int mt = 0; mt < 2; ++mt) xacc[mt] = __builtin_amdgcn_mfma_f32_16x16x32_bf16(ck_frag(qlo[ks][mt].x, qlo[ks][mt].y, qhi[ks][mt].x, qhi[ks][mt].y), Bs, xacc[mt], 0, 0, 0);
;     }
;     f32x4 Z = __builtin_amdgcn_mfma_f32_16x16x32_bf16(ck_frag(0u, 0u, mk.x, mk.y), ck_frag(0u, 0u, vq.x, vq.y), xacc[0], 0, 0, 0);
; #pragma unroll
;     for (int j = 0; j < 4; ++j) Z = __builtin_amdgcn_mfma_f32_16x16x32_bf16(ck_frag(mn[j].x, mn[j].y, 0u, 0u), ck_frag(pkc(Z[0], Z[1]), pkc(Z[2], Z[3]), vq.x, vq.y), Z, 0, 0, 0);
;     const pg8::bf16x8 UV = ck_frag(pkc(Z[0], Z[1]), pkc(Z[2], Z[3]), vq.x, vq.y);
;     { const f32x4 y = __builtin_amdgcn_mfma_f32_16x16x32_bf16(ck_frag(ylo.x, ylo.y, yhi.x, yhi.y), UV, xacc[1], 0, 0, 0);
;       yout = y; vout = vq; dout = *(const LAS f32x4*)(slot + CK_DOT + 16 * g);
; #pragma unroll
;       for (int r = 0; r < 4; ++r) { const float s1 = allred16(y[r]), s2 = allred16(y[r] * y[r]); if (n == 0) *(LAS f2*)(st + ((4 * g + r) * 4 + cw) * 8) = (f2){s1, s2}; } }
; #pragma unroll
.LBB0_118:
	s_andn2_b64 vcc, exec, s[34:35]
	s_cbranch_vccnz .LBB0_115
	s_and_b32 s2, s29, 4
	s_lshl_b32 s7, s2, 14
	s_add_i32 s7, s7, 0
	v_add_u32_e32 v32, s7, v166
	v_add_u32_e32 v33, v32, v167
	ds_read2_b64 v[36:39], v33 offset1:4
	v_add_u32_e32 v34, 0x800, v33
	s_waitcnt vmcnt(3)
	v_add_u32_e32 v44, v32, v169
	ds_read2_b64 v[40:43], v34 offset0:16 offset1:20
	ds_read2_b64 v[64:67], v33 offset0:8 offset1:12
	ds_read2_b64 v[68:71], v34 offset0:24 offset1:28
	v_add_u32_e32 v34, 0x2800, v44
	ds_read2_b64 v[72:75], v34 offset0:160 offset1:240
	s_waitcnt vmcnt(1)
	v_cvt_pk_bf16_f32 v104, v92, v93
	s_waitcnt vmcnt(0)
	v_cvt_pk_bf16_f32 v105, v94, v95
	v_cvt_pk_bf16_f32 v106, v88, v89
	v_cvt_pk_bf16_f32 v107, v90, v91
	v_add_u32_e32 v33, v32, v168
	v_add_u32_e32 v34, 0x3000, v44
	s_waitcnt lgkmcnt(4)
	v_mfma_f32_16x16x32_bf16 v[36:39], v[36:39], v[104:107], 0
	ds_read2_b64 v[76:79], v34 offset0:64 offset1:144
	ds_read_b64 v[34:35], v33 offset:8960
	ds_read_b64 v[96:97], v44 offset:14080
	v_add3_u32 v33, s7, v170, v166
	v_add_u32_e32 v33, 0x3800, v33
	s_waitcnt lgkmcnt(6)
	v_mfma_f32_16x16x32_bf16 v[40:43], v[40:43], v[104:107], 0
	v_cvt_pk_bf16_f32 v104, v84, v85
	v_cvt_pk_bf16_f32 v105, v86, v87
	v_cvt_pk_bf16_f32 v106, v80, v81
	v_cvt_pk_bf16_f32 v107, v82, v83
	ds_read2_b64 v[100:103], v33 offset0:48 offset1:52
	v_add_u32_e32 v33, v32, v170
	s_waitcnt lgkmcnt(6)
	v_mfma_f32_16x16x32_bf16 v[36:39], v[64:67], v[104:107], v[36:39]
	v_mov_b32_e32 v64, v129
	v_mov_b32_e32 v65, v129
	s_waitcnt lgkmcnt(4)
	v_mov_b32_e32 v66, v72
	v_mov_b32_e32 v67, v73
	v_add_u32_e32 v108, s7, v171
	v_add_u32_e32 v44, 0x1000, v33
	v_add_u32_e32 v33, 0x1800, v33
	ds_read2_b64 v[56:59], v44 offset0:32 offset1:36
	ds_read2_b64 v[52:55], v44 offset0:176 offset1:180
	ds_read_b128 v[48:51], v108 offset:15872
	ds_read_b128 v[44:47], v108 offset:15936
	ds_read2_b64 v[60:63], v33 offset0:64 offset1:68
	v_add_u32_e32 v72, v32, v172
	v_mov_b32_e32 v32, v129
	v_mov_b32_e32 v33, v129
	v_mfma_f32_16x16x32_bf16 v[40:43], v[68:71], v[104:107], v[40:43]
	s_waitcnt lgkmcnt(8)
	v_mov_b32_e32 v68, v76
	v_mov_b32_e32 v69, v77
	v_mov_b32_e32 v70, v129
	s_waitcnt lgkmcnt(7)
	v_mfma_f32_16x16x32_bf16 v[36:39], v[64:67], v[32:35], v[36:39]
	v_mov_b32_e32 v64, v74
	v_mov_b32_e32 v65, v75
	v_mov_b32_e32 v66, v129
	v_mov_b32_e32 v67, v129
	v_mov_b32_e32 v71, v129
	s_nop 2
	v_cvt_pk_bf16_f32 v32, v36, v37
	v_cvt_pk_bf16_f32 v33, v38, v39
	v_mov_b32_e32 v98, v129
	v_mov_b32_e32 v99, v129
	v_mfma_f32_16x16x32_bf16 v[36:39], v[64:67], v[32:35], v[36:39]
	v_mov_b32_e32 v64, v78
	v_mov_b32_e32 v65, v79
	v_add_u32_e32 v72, 0x1000, v72
	s_lshl_b32 s33, s2, 9
	s_add_i32 s33, s33, 0
	s_nop 2
	v_cvt_pk_bf16_f32 v32, v36, v37
	v_cvt_pk_bf16_f32 v33, v38, v39
	s_add_i32 s33, s33, 0x24800
	s_nop 0
	v_mfma_f32_16x16x32_bf16 v[36:39], v[68:71], v[32:35], v[36:39]
	s_nop 7
	v_cvt_pk_bf16_f32 v32, v36, v37
	v_cvt_pk_bf16_f32 v33, v38, v39
	s_nop 1
	v_mfma_f32_16x16x32_bf16 v[36:39], v[64:67], v[32:35], v[36:39]
	ds_read2_b64 v[64:67], v72 offset0:32 offset1:36
	ds_read_b128 v[76:79], v108 offset:16000
	ds_read_b128 v[72:75], v108 offset:16064
	s_nop 4
	v_cvt_pk_bf16_f32 v32, v36, v37
	v_cvt_pk_bf16_f32 v33, v38, v39
	s_waitcnt lgkmcnt(9)
	s_nop 0
	v_mfma_f32_16x16x32_bf16 v[36:39], v[96:99], v[32:35], v[36:39]
	v_add_u32_e32 v96, s33, v173
	s_nop 6
	v_cvt_pk_bf16_f32 v32, v36, v37
	v_cvt_pk_bf16_f32 v33, v38, v39
	ds_read_b128 v[36:39], v108 offset:16128
	s_waitcnt lgkmcnt(9)
	v_mfma_f32_16x16x32_bf16 v[40:43], v[100:103], v[32:35], v[40:43]
	s_waitcnt lgkmcnt(4)
	v_mfma_f32_16x16x32_bf16 v[56:59], v[56:59], v[32:35], v[92:95]
	s_waitcnt lgkmcnt(3)
	v_mfma_f32_16x16x32_bf16 v[52:55], v[52:55], v[32:35], v[88:91]
	s_waitcnt lgkmcnt(0)
	v_mfma_f32_16x16x32_bf16 v[60:63], v[60:63], v[32:35], v[84:87]
	s_waitcnt lgkmcnt(0)
	v_mfma_f32_16x16x32_bf16 v[80:83], v[64:67], v[32:35], v[80:83]
	s_nop 7
	v_mul_f32_e32 v71, v40, v40
	v_mov_b32_dpp v68, v40 quad_perm:[1,0,3,2] row_mask:0xf bank_mask:0xf bound_ctrl:1
	v_mov_b32_e32 v70, v40
	v_mov_b32_dpp v69, v71 quad_perm:[1,0,3,2] row_mask:0xf bank_mask:0xf bound_ctrl:1
	v_pk_add_f32 v[68:69], v[70:71], v[68:69]
	s_nop 1
	v_mov_b32_dpp v70, v68 quad_perm:[2,3,0,1] row_mask:0xf bank_mask:0xf bound_ctrl:1
	v_mov_b32_dpp v71, v69 quad_perm:[2,3,0,1] row_mask:0xf bank_mask:0xf bound_ctrl:1
	v_pk_add_f32 v[68:69], v[68:69], v[70:71]
	s_nop 1
	v_mov_b32_dpp v70, v68 row_half_mirror row_mask:0xf bank_mask:0xf bound_ctrl:1
	v_mov_b32_dpp v71, v69 row_half_mirror row_mask:0xf bank_mask:0xf bound_ctrl:1
	v_pk_add_f32 v[68:69], v[68:69], v[70:71]
	s_nop 1
	v_mov_b32_dpp v70, v68 row_mirror row_mask:0xf bank_mask:0xf bound_ctrl:1
	v_mov_b32_dpp v71, v69 row_mirror row_mask:0xf bank_mask:0xf bound_ctrl:1
	s_and_saveexec_b64 s[34:35], s[40:41]
	v_pk_add_f32 v[68:69], v[68:69], v[70:71]
	ds_write_b64 v96, v[68:69]
	s_or_b64 exec, exec, s[34:35]
	v_mul_f32_e32 v71, v41, v41
	v_mov_b32_dpp v68, v41 quad_perm:[1,0,3,2] row_mask:0xf bank_mask:0xf bound_ctrl:1
	v_mov_b32_e32 v70, v41
	v_mov_b32_dpp v69, v71 quad_perm:[1,0,3,2] row_mask:0xf bank_mask:0xf bound_ctrl:1
	v_pk_add_f32 v[68:69], v[70:71], v[68:69]
	s_nop 1
	v_mov_b32_dpp v70, v68 quad_perm:[2,3,0,1] row_mask:0xf bank_mask:0xf bound_ctrl:1
	v_mov_b32_dpp v71, v69 quad_perm:[2,3,0,1] row_mask:0xf bank_mask:0xf bound_ctrl:1
	v_pk_add_f32 v[68:69], v[68:69], v[70:71]
	s_nop 1
	v_mov_b32_dpp v70, v68 row_half_mirror row_mask:0xf bank_mask:0xf bound_ctrl:1
	v_mov_b32_dpp v71, v69 row_half_mirror row_mask:0xf bank_mask:0xf bound_ctrl:1
	v_pk_add_f32 v[68:69], v[68:69], v[70:71]
	s_nop 1
	v_mov_b32_dpp v70, v68 row_mirror row_mask:0xf bank_mask:0xf bound_ctrl:1
; #define LAS __attribute__((address_space(3)))
; __device__ __forceinline__ void ck_consume(const LAS unsigned char* slot, f32x4 (&sacc)[4], LAS unsigned char* st  , int lane, int cw, f32x4& yout, u32x2& vout, f32x4& dout) {
;     ...
;         for (int mt = 0; mt < 2; ++mt) { const LAS unsigned char* p = slot + CK_QR + (16 * mt + n) * 136 + (32 * ks + 4 * g) * 2; qlo[ks][mt] = ck_ld8(p); qhi[ks][mt] = ck_ld8(p + 32); }
;     const u32x2 vq = ck_ld8(slot + CK_VT + (16 * cw + n) * 40 + 8 * g);
;     const u32x2 mk = ck_ld8(slot + CK_MK + n * 40 + 8 * g);
; #pragma unroll
;     for (int j = 0; j < 4; ++j) mn[j] = ck_ld8(slot + CK_MN + j * 640 + n * 40 + 8 * g);
;     const u32x2 ylo = ck_ld8(slot + CK_MY + n * 72 + 8 * g), yhi = ck_ld8(slot + CK_MY + n * 72 + 8 * g + 32);
; #pragma unroll
;     for (int kb = 0; kb < 4; ++kb) { const LAS unsigned char* p = slot + CK_BK + (16 * kb + n) * 72 + 8 * g; blo[kb] = ck_ld8(p); bhi[kb] = ck_ld8(p + 32); gm[kb] = *(const LAS f32x4*)(slot + CK_GM + (16 * kb + 4 * g) * 4); }
;     f32x4 xacc[2] = {zero4, zero4};
; #pragma unroll
;     for (int ks = 0; ks < 2; ++ks) {
;         const pg8::bf16x8 Bs = ck_frag(pkc(sacc[2 * ks][0], sacc[2 * ks][1]), pkc(sacc[2 * ks][2], sacc[2 * ks][3]), pkc(sacc[2 * ks + 1][0], sacc[2 * ks + 1][1]), pkc(sacc[2 * ks + 1][2], sacc[2 * ks + 1][3]));
; #pragma unroll
;         for (int mt = 0; mt < 2; ++mt) xacc[mt] = __builtin_amdgcn_mfma_f32_16x16x32_bf16(ck_frag(qlo[ks][mt].x, qlo[ks][mt].y, qhi[ks][mt].x, qhi[ks][mt].y), Bs, xacc[mt], 0, 0, 0);
;     }
;     f32x4 Z = __builtin_amdgcn_mfma_f32_16x16x32_bf16(ck_frag(0u, 0u, mk.x, mk.y), ck_frag(0u, 0u, vq.x, vq.y), xacc[0], 0, 0, 0);
; #pragma unroll
;     for (int j = 0; j < 4; ++j) Z = __builtin_amdgcn_mfma_f32_16x16x32_bf16(ck_frag(mn[j].x, mn[j].y, 0u, 0u), ck_frag(pkc(Z[0], Z[1]), pkc(Z[2], Z[3]), vq.x, vq.y), Z, 0, 0, 0);
;     const pg8::bf16x8 UV = ck_frag(pkc(Z[0], Z[1]), pkc(Z[2], Z[3]), vq.x, vq.y);
;     { const f32x4 y = __builtin_amdgcn_mfma_f32_16x16x32_bf16(ck_frag(ylo.x, ylo.y, yhi.x, yhi.y), UV, xacc[1], 0, 0, 0);
;       yout = y; vout = vq; dout = *(const LAS f32x4*)(slot + CK_DOT + 16 * g);
; #pragma unroll
;       for (int r = 0; r < 4; ++r) { const float s1 = allred16(y[r]), s2 = allred16(y[r] * y[r]); if (n == 0) *(LAS f2*)(st + ((4 * g + r) * 4 + cw) * 8) = (f2){s1, s2}; } }
; #pragma unroll
	v_mov_b32_dpp v71, v69 row_mirror row_mask:0xf bank_mask:0xf bound_ctrl:1
	s_and_saveexec_b64 s[34:35], s[40:41]
	v_pk_add_f32 v[68:69], v[68:69], v[70:71]
	ds_write_b64 v96, v[68:69] offset:32
	s_or_b64 exec, exec, s[34:35]
	v_mul_f32_e32 v71, v42, v42
	v_mov_b32_dpp v68, v42 quad_perm:[1,0,3,2] row_mask:0xf bank_mask:0xf bound_ctrl:1
	v_mov_b32_e32 v70, v42
	v_mov_b32_dpp v69, v71 quad_perm:[1,0,3,2] row_mask:0xf bank_mask:0xf bound_ctrl:1
	v_pk_add_f32 v[68:69], v[70:71], v[68:69]
	s_nop 1
	v_mov_b32_dpp v70, v68 quad_perm:[2,3,0,1] row_mask:0xf bank_mask:0xf bound_ctrl:1
	v_mov_b32_dpp v71, v69 quad_perm:[2,3,0,1] row_mask:0xf bank_mask:0xf bound_ctrl:1
	v_pk_add_f32 v[68:69], v[68:69], v[70:71]
	s_nop 1
	v_mov_b32_dpp v70, v68 row_half_mirror row_mask:0xf bank_mask:0xf bound_ctrl:1
	v_mov_b32_dpp v71, v69 row_half_mirror row_mask:0xf bank_mask:0xf bound_ctrl:1
	v_pk_add_f32 v[68:69], v[68:69], v[70:71]
	s_nop 1
	v_mov_b32_dpp v70, v68 row_mirror row_mask:0xf bank_mask:0xf bound_ctrl:1
	v_mov_b32_dpp v71, v69 row_mirror row_mask:0xf bank_mask:0xf bound_ctrl:1
	s_and_saveexec_b64 s[34:35], s[40:41]
	v_pk_add_f32 v[68:69], v[68:69], v[70:71]
	ds_write_b64 v96, v[68:69] offset:64
	s_or_b64 exec, exec, s[34:35]
	v_mul_f32_e32 v71, v43, v43
	v_mov_b32_dpp v68, v43 quad_perm:[1,0,3,2] row_mask:0xf bank_mask:0xf bound_ctrl:1
	v_mov_b32_e32 v70, v43
	v_mov_b32_dpp v69, v71 quad_perm:[1,0,3,2] row_mask:0xf bank_mask:0xf bound_ctrl:1
	v_pk_add_f32 v[68:69], v[70:71], v[68:69]
	s_nop 1
	v_mov_b32_dpp v70, v68 quad_perm:[2,3,0,1] row_mask:0xf bank_mask:0xf bound_ctrl:1
	v_mov_b32_dpp v71, v69 quad_perm:[2,3,0,1] row_mask:0xf bank_mask:0xf bound_ctrl:1
	v_pk_add_f32 v[68:69], v[68:69], v[70:71]
	s_nop 1
	v_mov_b32_dpp v70, v68 row_half_mirror row_mask:0xf bank_mask:0xf bound_ctrl:1
	v_mov_b32_dpp v71, v69 row_half_mirror row_mask:0xf bank_mask:0xf bound_ctrl:1
	v_pk_add_f32 v[68:69], v[68:69], v[70:71]
	s_nop 1
	v_mov_b32_dpp v70, v68 row_mirror row_mask:0xf bank_mask:0xf bound_ctrl:1
	v_mov_b32_dpp v71, v69 row_mirror row_mask:0xf bank_mask:0xf bound_ctrl:1
	s_and_saveexec_b64 s[34:35], s[40:41]
	v_pk_add_f32 v[68:69], v[68:69], v[70:71]
	ds_write_b64 v96, v[68:69] offset:96
	s_or_b64 exec, exec, s[34:35]
	v_ashrrev_i32_e32 v71, 31, v128
	v_mov_b32_e32 v70, v128
	v_lshl_add_u64 v[158:159], v[70:71], 1, v[156:157]
	s_movk_i32 s7, 0x2000
	v_add_co_u32_e32 v70, vcc, s7, v158
	s_movk_i32 s7, 0x3000
	s_nop 0
	v_addc_co_u32_e32 v71, vcc, 0, v159, vcc
	v_lshl_add_u64 v[68:69], v[128:129], 1, v[156:157]
	global_load_ushort v232, v[70:71], off offset:-4096
	global_load_ushort v233, v[70:71], off
	v_mov_b32_e32 v110, v129
	s_waitcnt lgkmcnt(6)
	s_nop 0
	v_pk_mul_f32 v[70:71], v[50:51], v[58:59]
	v_mov_b32_e32 v111, v129
	v_cvt_pk_bf16_f32 v117, v70, v71
	v_add_co_u32_e32 v32, vcc, s7, v158
	s_or_b32 s7, s2, 1
	s_nop 0
	v_addc_co_u32_e32 v33, vcc, 0, v159, vcc
	global_load_ushort v234, v[68:69], off
	global_load_ushort v235, v[32:33], off
	s_lshl_b32 s33, s7, 14
	s_add_i32 s33, s33, 0
	v_add_u32_e32 v32, s33, v166
	v_add_u32_e32 v33, v32, v167
	v_pk_mul_f32 v[68:69], v[48:49], v[56:57]
	ds_read2_b64 v[48:51], v33 offset1:4
	v_pk_mul_f32 v[64:65], v[44:45], v[52:53]
	v_add_u32_e32 v44, 0x800, v33
	v_pk_mul_f32 v[66:67], v[46:47], v[54:55]
	ds_read2_b64 v[52:55], v44 offset0:16 offset1:20
	ds_read2_b64 v[92:95], v33 offset0:8 offset1:12
	ds_read2_b64 v[96:99], v44 offset0:24 offset1:28
	v_add_u32_e32 v44, v32, v169
	v_add_u32_e32 v45, 0x2800, v44
	ds_read2_b64 v[100:103], v45 offset0:160 offset1:240
	v_cvt_pk_bf16_f32 v116, v68, v69
	v_cvt_pk_bf16_f32 v118, v64, v65
	v_cvt_pk_bf16_f32 v119, v66, v67
	s_waitcnt lgkmcnt(7)
	v_pk_mul_f32 v[62:63], v[78:79], v[62:63]
	v_pk_mul_f32 v[60:61], v[76:77], v[60:61]
	s_waitcnt lgkmcnt(4)
	v_mfma_f32_16x16x32_bf16 v[48:51], v[48:51], v[116:119], 0
	v_mul_f32_e64 v58, v74, v82
	v_mul_f32_e64 v59, v75, v83
	v_pk_mul_f32 v[56:57], v[72:73], v[80:81]
	v_add_u32_e32 v33, v32, v168
	s_waitcnt lgkmcnt(3)
	v_mfma_f32_16x16x32_bf16 v[52:55], v[52:55], v[116:119], 0
	v_cvt_pk_bf16_f32 v116, v60, v61
	v_cvt_pk_bf16_f32 v117, v62, v63
	v_cvt_pk_bf16_f32 v118, v56, v57
	v_cvt_pk_bf16_f32 v119, v58, v59
	v_add_u32_e32 v45, 0x3000, v44
	ds_read2_b64 v[104:107], v45 offset0:64 offset1:144
	ds_read_b64 v[46:47], v33 offset:8960
	ds_read_b64 v[108:109], v44 offset:14080
	s_waitcnt lgkmcnt(5)
	v_mfma_f32_16x16x32_bf16 v[48:51], v[92:95], v[116:119], v[48:51]
	v_mov_b32_e32 v92, v129
	v_mov_b32_e32 v93, v129
	s_waitcnt lgkmcnt(3)
	v_mov_b32_e32 v94, v100
	v_mov_b32_e32 v95, v101
	v_add3_u32 v33, s33, v170, v166
	v_add_u32_e32 v33, 0x3800, v33
	v_add_u32_e32 v44, v32, v170
	ds_read2_b64 v[112:115], v33 offset0:48 offset1:52
	v_add_u32_e32 v33, s33, v171
	v_add_u32_e32 v45, 0x1000, v44
	v_add_u32_e32 v44, 0x1800, v44
	ds_read2_b64 v[88:91], v45 offset0:32 offset1:36
	ds_read2_b64 v[80:83], v45 offset0:176 offset1:180
	ds_read_b128 v[76:79], v33 offset:15872
	ds_read_b128 v[72:75], v33 offset:15936
	ds_read2_b64 v[84:87], v44 offset0:64 offset1:68
	v_mov_b32_e32 v44, v129
	v_mov_b32_e32 v45, v129
	v_mfma_f32_16x16x32_bf16 v[52:55], v[96:99], v[116:119], v[52:55]
	s_waitcnt lgkmcnt(8)
	v_mov_b32_e32 v96, v104
	v_mov_b32_e32 v97, v105
	v_mov_b32_e32 v98, v129
	s_waitcnt lgkmcnt(7)
; #define LAS __attribute__((address_space(3)))
; __device__ __forceinline__ float allred16(float x) { x += dpp_f<0xB1>(x); x += dpp_f<0x4E>(x); x += dpp_f<0x141>(x); x += dpp_f<0x140>(x); return x; }
; __device__ __forceinline__ unsigned pkc(float lo, float hi) { f2 v = {lo, hi}; return __builtin_bit_cast(unsigned, __builtin_convertvector(v, bf16x2_t)); }
; __device__ __forceinline__ void ck_consume(const LAS unsigned char* slot, f32x4 (&sacc)[4], LAS unsigned char* st  , int lane, int cw, f32x4& yout, u32x2& vout, f32x4& dout) {
;     ...
;         for (int mt = 0; mt < 2; ++mt) xacc[mt] = __builtin_amdgcn_mfma_f32_16x16x32_bf16(ck_frag(qlo[ks][mt].x, qlo[ks][mt].y, qhi[ks][mt].x, qhi[ks][mt].y), Bs, xacc[mt], 0, 0, 0);
;     }
;     f32x4 Z = __builtin_amdgcn_mfma_f32_16x16x32_bf16(ck_frag(0u, 0u, mk.x, mk.y), ck_frag(0u, 0u, vq.x, vq.y), xacc[0], 0, 0, 0);
; #pragma unroll
;     for (int j = 0; j < 4; ++j) Z = __builtin_amdgcn_mfma_f32_16x16x32_bf16(ck_frag(mn[j].x, mn[j].y, 0u, 0u), ck_frag(pkc(Z[0], Z[1]), pkc(Z[2], Z[3]), vq.x, vq.y), Z, 0, 0, 0);
;     const pg8::bf16x8 UV = ck_frag(pkc(Z[0], Z[1]), pkc(Z[2], Z[3]), vq.x, vq.y);
;     { const f32x4 y = __builtin_amdgcn_mfma_f32_16x16x32_bf16(ck_frag(ylo.x, ylo.y, yhi.x, yhi.y), UV, xacc[1], 0, 0, 0);
;       yout = y; vout = vq; dout = *(const LAS f32x4*)(slot + CK_DOT + 16 * g);
; #pragma unroll
;       for (int r = 0; r < 4; ++r) { const float s1 = allred16(y[r]), s2 = allred16(y[r] * y[r]); if (n == 0) *(LAS f2*)(st + ((4 * g + r) * 4 + cw) * 8) = (f2){s1, s2}; } }
; #pragma unroll
;     for (int kb = 0; kb < 4; ++kb) sacc[kb] = __builtin_amdgcn_mfma_f32_16x16x32_bf16(ck_frag(blo[kb].x, blo[kb].y, bhi[kb].x, bhi[kb].y), UV, sacc[kb], 0, 0, 0) * gm[kb];
	v_mfma_f32_16x16x32_bf16 v[48:51], v[92:95], v[44:47], v[48:51]
	v_mov_b32_e32 v92, v102
	v_mov_b32_e32 v93, v103
	v_mov_b32_e32 v94, v129
	v_mov_b32_e32 v95, v129
	v_mov_b32_e32 v99, v129
	s_nop 2
	v_cvt_pk_bf16_f32 v44, v48, v49
	v_cvt_pk_bf16_f32 v45, v50, v51
	v_add_u32_e32 v32, v32, v172
	v_add_u32_e32 v32, 0x1000, v32
	v_mfma_f32_16x16x32_bf16 v[48:51], v[92:95], v[44:47], v[48:51]
	v_mov_b32_e32 v92, v106
	v_mov_b32_e32 v93, v107
	ds_read2_b64 v[100:103], v32 offset0:32 offset1:36
	s_lshl_b32 s7, s7, 9
	s_add_i32 s7, s7, 0
	s_nop 2
	v_cvt_pk_bf16_f32 v44, v48, v49
	v_cvt_pk_bf16_f32 v45, v50, v51
	s_add_i32 s7, s7, 0x24800
	v_add_u32_e32 v106, s7, v173
	v_mfma_f32_16x16x32_bf16 v[48:51], v[96:99], v[44:47], v[48:51]
	s_nop 7
	v_cvt_pk_bf16_f32 v44, v48, v49
	v_cvt_pk_bf16_f32 v45, v50, v51
	s_nop 1
	v_mfma_f32_16x16x32_bf16 v[48:51], v[92:95], v[44:47], v[48:51]
	ds_read_b128 v[96:99], v33 offset:16000
	ds_read_b128 v[92:95], v33 offset:16064
	s_nop 5
	v_cvt_pk_bf16_f32 v44, v48, v49
	v_cvt_pk_bf16_f32 v45, v50, v51
	s_waitcnt lgkmcnt(9)
	s_nop 0
	v_mfma_f32_16x16x32_bf16 v[48:51], v[108:111], v[44:47], v[48:51]
	s_nop 7
	v_cvt_pk_bf16_f32 v44, v48, v49
	v_cvt_pk_bf16_f32 v45, v50, v51
	ds_read_b128 v[48:51], v33 offset:16128
	s_waitcnt lgkmcnt(9)
	v_mfma_f32_16x16x32_bf16 v[52:55], v[112:115], v[44:47], v[52:55]
	s_waitcnt lgkmcnt(3)
	v_mfma_f32_16x16x32_bf16 v[64:67], v[80:83], v[44:47], v[64:67]
	v_mfma_f32_16x16x32_bf16 v[68:71], v[88:91], v[44:47], v[68:71]
	s_waitcnt lgkmcnt(0)
	v_mfma_f32_16x16x32_bf16 v[60:63], v[84:87], v[44:47], v[60:63]
	s_waitcnt lgkmcnt(0)
	v_mfma_f32_16x16x32_bf16 v[56:59], v[100:103], v[44:47], v[56:59]
	s_nop 7
	v_mul_f32_e32 v105, v52, v52
	v_mov_b32_dpp v32, v52 quad_perm:[1,0,3,2] row_mask:0xf bank_mask:0xf bound_ctrl:1
	v_mov_b32_e32 v104, v52
	v_mov_b32_dpp v33, v105 quad_perm:[1,0,3,2] row_mask:0xf bank_mask:0xf bound_ctrl:1
	v_pk_add_f32 v[32:33], v[104:105], v[32:33]
	s_nop 1
	v_mov_b32_dpp v104, v32 quad_perm:[2,3,0,1] row_mask:0xf bank_mask:0xf bound_ctrl:1
	v_mov_b32_dpp v105, v33 quad_perm:[2,3,0,1] row_mask:0xf bank_mask:0xf bound_ctrl:1
	v_pk_add_f32 v[32:33], v[32:33], v[104:105]
	s_nop 1
	v_mov_b32_dpp v104, v32 row_half_mirror row_mask:0xf bank_mask:0xf bound_ctrl:1
	v_mov_b32_dpp v105, v33 row_half_mirror row_mask:0xf bank_mask:0xf bound_ctrl:1
	v_pk_add_f32 v[32:33], v[32:33], v[104:105]
	s_nop 1
	v_mov_b32_dpp v104, v32 row_mirror row_mask:0xf bank_mask:0xf bound_ctrl:1
	v_mov_b32_dpp v105, v33 row_mirror row_mask:0xf bank_mask:0xf bound_ctrl:1
	s_and_saveexec_b64 s[34:35], s[40:41]
	v_pk_add_f32 v[32:33], v[32:33], v[104:105]
	ds_write_b64 v106, v[32:33]
	s_or_b64 exec, exec, s[34:35]
	v_mul_f32_e32 v105, v53, v53
	v_mov_b32_dpp v32, v53 quad_perm:[1,0,3,2] row_mask:0xf bank_mask:0xf bound_ctrl:1
	v_mov_b32_e32 v104, v53
	v_mov_b32_dpp v33, v105 quad_perm:[1,0,3,2] row_mask:0xf bank_mask:0xf bound_ctrl:1
	v_pk_add_f32 v[32:33], v[104:105], v[32:33]
	s_nop 1
	v_mov_b32_dpp v104, v32 quad_perm:[2,3,0,1] row_mask:0xf bank_mask:0xf bound_ctrl:1
	v_mov_b32_dpp v105, v33 quad_perm:[2,3,0,1] row_mask:0xf bank_mask:0xf bound_ctrl:1
	v_pk_add_f32 v[32:33], v[32:33], v[104:105]
	s_nop 1
	v_mov_b32_dpp v104, v32 row_half_mirror row_mask:0xf bank_mask:0xf bound_ctrl:1
	v_mov_b32_dpp v105, v33 row_half_mirror row_mask:0xf bank_mask:0xf bound_ctrl:1
	v_pk_add_f32 v[32:33], v[32:33], v[104:105]
	s_nop 1
	v_mov_b32_dpp v104, v32 row_mirror row_mask:0xf bank_mask:0xf bound_ctrl:1
	v_mov_b32_dpp v105, v33 row_mirror row_mask:0xf bank_mask:0xf bound_ctrl:1
	s_and_saveexec_b64 s[34:35], s[40:41]
	v_pk_add_f32 v[32:33], v[32:33], v[104:105]
	ds_write_b64 v106, v[32:33] offset:32
	s_or_b64 exec, exec, s[34:35]
	v_mul_f32_e32 v105, v54, v54
	v_mov_b32_dpp v32, v54 quad_perm:[1,0,3,2] row_mask:0xf bank_mask:0xf bound_ctrl:1
	v_mov_b32_e32 v104, v54
	v_mov_b32_dpp v33, v105 quad_perm:[1,0,3,2] row_mask:0xf bank_mask:0xf bound_ctrl:1
	v_pk_add_f32 v[32:33], v[104:105], v[32:33]
	s_nop 1
	v_mov_b32_dpp v104, v32 quad_perm:[2,3,0,1] row_mask:0xf bank_mask:0xf bound_ctrl:1
	v_mov_b32_dpp v105, v33 quad_perm:[2,3,0,1] row_mask:0xf bank_mask:0xf bound_ctrl:1
	v_pk_add_f32 v[32:33], v[32:33], v[104:105]
	s_nop 1
	v_mov_b32_dpp v104, v32 row_half_mirror row_mask:0xf bank_mask:0xf bound_ctrl:1
	v_mov_b32_dpp v105, v33 row_half_mirror row_mask:0xf bank_mask:0xf bound_ctrl:1
	v_pk_add_f32 v[32:33], v[32:33], v[104:105]
	s_nop 1
	v_mov_b32_dpp v104, v32 row_mirror row_mask:0xf bank_mask:0xf bound_ctrl:1
	v_mov_b32_dpp v105, v33 row_mirror row_mask:0xf bank_mask:0xf bound_ctrl:1
	s_and_saveexec_b64 s[34:35], s[40:41]
	v_pk_add_f32 v[32:33], v[32:33], v[104:105]
	ds_write_b64 v106, v[32:33] offset:64
	s_or_b64 exec, exec, s[34:35]
	v_mul_f32_e32 v105, v55, v55
	v_mov_b32_dpp v32, v55 quad_perm:[1,0,3,2] row_mask:0xf bank_mask:0xf bound_ctrl:1
	v_mov_b32_e32 v104, v55
	v_mov_b32_dpp v33, v105 quad_perm:[1,0,3,2] row_mask:0xf bank_mask:0xf bound_ctrl:1
	v_pk_add_f32 v[32:33], v[104:105], v[32:33]
	s_nop 1
	v_mov_b32_dpp v104, v32 quad_perm:[2,3,0,1] row_mask:0xf bank_mask:0xf bound_ctrl:1
	v_mov_b32_dpp v105, v33 quad_perm:[2,3,0,1] row_mask:0xf bank_mask:0xf bound_ctrl:1
	v_pk_add_f32 v[32:33], v[32:33], v[104:105]
	s_nop 1
	v_mov_b32_dpp v104, v32 row_half_mirror row_mask:0xf bank_mask:0xf bound_ctrl:1
	v_mov_b32_dpp v105, v33 row_half_mirror row_mask:0xf bank_mask:0xf bound_ctrl:1
	v_pk_add_f32 v[32:33], v[32:33], v[104:105]
	s_nop 1
	v_mov_b32_dpp v104, v32 row_mirror row_mask:0xf bank_mask:0xf bound_ctrl:1
	v_mov_b32_dpp v105, v33 row_mirror row_mask:0xf bank_mask:0xf bound_ctrl:1
	s_and_saveexec_b64 s[34:35], s[40:41]
	v_pk_add_f32 v[32:33], v[32:33], v[104:105]
	ds_write_b64 v106, v[32:33] offset:96
	s_or_b64 exec, exec, s[34:35]
	v_add_co_u32_e32 v32, vcc, 0x10000, v158
	v_addc_co_u32_e32 v33, vcc, 0, v159, vcc
	v_add_co_u32_e32 v80, vcc, 0x11000, v158
	s_nop 0
	v_addc_co_u32_e32 v81, vcc, 0, v159, vcc
	s_or_b32 s7, s2, 2
	s_lshl_b32 s33, s7, 14
	s_add_i32 s33, s33, 0
	v_mov_b32_e32 v122, v129
	v_add_co_u32_e32 v44, vcc, 0x12000, v158
	v_mov_b32_e32 v123, v129
	s_nop 0
	v_addc_co_u32_e32 v45, vcc, 0, v159, vcc
	v_add_co_u32_e32 v82, vcc, 0x13000, v158
	s_lshl_b32 s7, s7, 9
	s_nop 0
	v_addc_co_u32_e32 v83, vcc, 0, v159, vcc
	global_load_ushort v236, v[32:33], off
	global_load_ushort v237, v[80:81], off
	global_load_ushort v238, v[44:45], off
	global_load_ushort v239, v[82:83], off
	v_add_u32_e32 v32, s33, v166
	v_add_u32_e32 v33, v32, v167
	v_pk_mul_f32 v[82:83], v[78:79], v[70:71]
	v_pk_mul_f32 v[80:81], v[76:77], v[68:69]
	v_pk_mul_f32 v[78:79], v[74:75], v[66:67]
	v_pk_mul_f32 v[76:77], v[72:73], v[64:65]
	s_waitcnt lgkmcnt(2)
; #define LAS __attribute__((address_space(3)))
; __device__ __forceinline__ void ck_consume(const LAS unsigned char* slot, f32x4 (&sacc)[4], LAS unsigned char* st  , int lane, int cw, f32x4& yout, u32x2& vout, f32x4& dout) {
;     ...
;         for (int mt = 0; mt < 2; ++mt) { const LAS unsigned char* p = slot + CK_QR + (16 * mt + n) * 136 + (32 * ks + 4 * g) * 2; qlo[ks][mt] = ck_ld8(p); qhi[ks][mt] = ck_ld8(p + 32); }
;     const u32x2 vq = ck_ld8(slot + CK_VT + (16 * cw + n) * 40 + 8 * g);
;     const u32x2 mk = ck_ld8(slot + CK_MK + n * 40 + 8 * g);
; #pragma unroll
;     for (int j = 0; j < 4; ++j) mn[j] = ck_ld8(slot + CK_MN + j * 640 + n * 40 + 8 * g);
;     const u32x2 ylo = ck_ld8(slot + CK_MY + n * 72 + 8 * g), yhi = ck_ld8(slot + CK_MY + n * 72 + 8 * g + 32);
; #pragma unroll
;     for (int kb = 0; kb < 4; ++kb) { const LAS unsigned char* p = slot + CK_BK + (16 * kb + n) * 72 + 8 * g; blo[kb] = ck_ld8(p); bhi[kb] = ck_ld8(p + 32); gm[kb] = *(const LAS f32x4*)(slot + CK_GM + (16 * kb + 4 * g) * 4); }
;     f32x4 xacc[2] = {zero4, zero4};
; #pragma unroll
;     for (int ks = 0; ks < 2; ++ks) {
;         const pg8::bf16x8 Bs = ck_frag(pkc(sacc[2 * ks][0], sacc[2 * ks][1]), pkc(sacc[2 * ks][2], sacc[2 * ks][3]), pkc(sacc[2 * ks + 1][0], sacc[2 * ks + 1][1]), pkc(sacc[2 * ks + 1][2], sacc[2 * ks + 1][3]));
; #pragma unroll
;         for (int mt = 0; mt < 2; ++mt) xacc[mt] = __builtin_amdgcn_mfma_f32_16x16x32_bf16(ck_frag(qlo[ks][mt].x, qlo[ks][mt].y, qhi[ks][mt].x, qhi[ks][mt].y), Bs, xacc[mt], 0, 0, 0);
;     }
;     f32x4 Z = __builtin_amdgcn_mfma_f32_16x16x32_bf16(ck_frag(0u, 0u, mk.x, mk.y), ck_frag(0u, 0u, vq.x, vq.y), xacc[0], 0, 0, 0);
; #pragma unroll
;     for (int j = 0; j < 4; ++j) Z = __builtin_amdgcn_mfma_f32_16x16x32_bf16(ck_frag(mn[j].x, mn[j].y, 0u, 0u), ck_frag(pkc(Z[0], Z[1]), pkc(Z[2], Z[3]), vq.x, vq.y), Z, 0, 0, 0);
;     const pg8::bf16x8 UV = ck_frag(pkc(Z[0], Z[1]), pkc(Z[2], Z[3]), vq.x, vq.y);
;     { const f32x4 y = __builtin_amdgcn_mfma_f32_16x16x32_bf16(ck_frag(ylo.x, ylo.y, yhi.x, yhi.y), UV, xacc[1], 0, 0, 0);
;       yout = y; vout = vq; dout = *(const LAS f32x4*)(slot + CK_DOT + 16 * g);
; #pragma unroll
;       for (int r = 0; r < 4; ++r) { const float s1 = allred16(y[r]), s2 = allred16(y[r] * y[r]); if (n == 0) *(LAS f2*)(st + ((4 * g + r) * 4 + cw) * 8) = (f2){s1, s2}; } }
; #pragma unroll
	v_pk_mul_f32 v[74:75], v[98:99], v[62:63]
	v_pk_mul_f32 v[72:73], v[96:97], v[60:61]
	ds_read2_b64 v[60:63], v33 offset1:4
	v_add_u32_e32 v44, 0x800, v33
	ds_read2_b64 v[64:67], v44 offset0:16 offset1:20
	ds_read2_b64 v[104:107], v33 offset0:8 offset1:12
	ds_read2_b64 v[108:111], v44 offset0:24 offset1:28
	v_add_u32_e32 v44, v32, v169
	v_add_u32_e32 v45, 0x2800, v44
	ds_read2_b64 v[112:115], v45 offset0:160 offset1:240
	v_cvt_pk_bf16_f32 v214, v80, v81
	v_cvt_pk_bf16_f32 v215, v82, v83
	v_cvt_pk_bf16_f32 v216, v76, v77
	v_cvt_pk_bf16_f32 v217, v78, v79
	s_waitcnt lgkmcnt(6)
	v_pk_mul_f32 v[70:71], v[94:95], v[58:59]
	v_pk_mul_f32 v[68:69], v[92:93], v[56:57]
	s_waitcnt lgkmcnt(4)
	v_mfma_f32_16x16x32_bf16 v[60:63], v[60:63], v[214:217], 0
	v_add_u32_e32 v45, 0x3000, v44
	v_add_u32_e32 v33, v32, v168
	ds_read2_b64 v[116:119], v45 offset0:64 offset1:144
	ds_read_b64 v[58:59], v33 offset:8960
	ds_read_b64 v[120:121], v44 offset:14080
	s_waitcnt lgkmcnt(6)
	v_mfma_f32_16x16x32_bf16 v[64:67], v[64:67], v[214:217], 0
	v_cvt_pk_bf16_f32 v214, v72, v73
	v_cvt_pk_bf16_f32 v215, v74, v75
	v_cvt_pk_bf16_f32 v216, v68, v69
	v_cvt_pk_bf16_f32 v217, v70, v71
	v_mov_b32_e32 v56, v129
	v_mov_b32_e32 v57, v129
	s_waitcnt lgkmcnt(5)
	v_mfma_f32_16x16x32_bf16 v[60:63], v[104:107], v[214:217], v[60:63]
	v_mov_b32_e32 v104, v129
	v_mov_b32_e32 v105, v129
	s_waitcnt lgkmcnt(3)
	v_mov_b32_e32 v106, v112
	v_mov_b32_e32 v107, v113
	v_mfma_f32_16x16x32_bf16 v[64:67], v[108:111], v[214:217], v[64:67]
	s_waitcnt lgkmcnt(2)
	v_mov_b32_e32 v108, v116
	v_mov_b32_e32 v109, v117
	v_mov_b32_e32 v110, v129
	s_waitcnt lgkmcnt(1)
	v_mfma_f32_16x16x32_bf16 v[60:63], v[104:107], v[56:59], v[60:63]
	v_mov_b32_e32 v104, v114
	v_mov_b32_e32 v105, v115
	v_mov_b32_e32 v106, v129
	v_mov_b32_e32 v107, v129
	v_mov_b32_e32 v111, v129
	s_nop 2
	v_cvt_pk_bf16_f32 v56, v60, v61
	v_cvt_pk_bf16_f32 v57, v62, v63
	v_add3_u32 v33, s33, v170, v166
	v_add_u32_e32 v33, 0x3800, v33
	v_mfma_f32_16x16x32_bf16 v[60:63], v[104:107], v[56:59], v[60:63]
	v_mov_b32_e32 v104, v118
	v_mov_b32_e32 v105, v119
	ds_read2_b64 v[124:127], v33 offset0:48 offset1:52
	v_add_u32_e32 v44, v32, v170
	v_add_u32_e32 v45, 0x1000, v44
	s_nop 2
	v_cvt_pk_bf16_f32 v56, v60, v61
	v_cvt_pk_bf16_f32 v57, v62, v63
	v_add_u32_e32 v32, v32, v172
	v_add_u32_e32 v33, s33, v171
	v_mfma_f32_16x16x32_bf16 v[60:63], v[108:111], v[56:59], v[60:63]
	ds_read2_b64 v[100:103], v45 offset0:32 offset1:36
	ds_read2_b64 v[92:95], v45 offset0:176 offset1:180
	v_add_u32_e32 v44, 0x1800, v44
	v_add_u32_e32 v32, 0x1000, v32
	ds_read_b128 v[88:91], v33 offset:15872
	ds_read_b128 v[84:87], v33 offset:15936
	s_nop 1
	v_cvt_pk_bf16_f32 v56, v60, v61
	v_cvt_pk_bf16_f32 v57, v62, v63
	ds_read2_b64 v[96:99], v44 offset0:64 offset1:68
	ds_read2_b64 v[112:115], v32 offset0:32 offset1:36
	v_mfma_f32_16x16x32_bf16 v[60:63], v[104:107], v[56:59], v[60:63]
	ds_read_b128 v[108:111], v33 offset:16000
	ds_read_b128 v[104:107], v33 offset:16064
	s_add_i32 s7, s7, 0
	s_add_i32 s7, s7, 0x24800
	v_add_u32_e32 v116, s7, v173
	s_nop 2
	v_cvt_pk_bf16_f32 v56, v60, v61
	v_cvt_pk_bf16_f32 v57, v62, v63
	s_waitcnt lgkmcnt(9)
	s_nop 0
	v_mfma_f32_16x16x32_bf16 v[60:63], v[120:123], v[56:59], v[60:63]
	s_nop 7
	v_cvt_pk_bf16_f32 v56, v60, v61
	v_cvt_pk_bf16_f32 v57, v62, v63
	ds_read_b128 v[60:63], v33 offset:16128
	s_waitcnt lgkmcnt(9)
	v_mfma_f32_16x16x32_bf16 v[64:67], v[124:127], v[56:59], v[64:67]
	s_waitcnt lgkmcnt(3)
	v_mfma_f32_16x16x32_bf16 v[76:79], v[92:95], v[56:59], v[76:79]
	v_mfma_f32_16x16x32_bf16 v[80:83], v[100:103], v[56:59], v[80:83]
	s_waitcnt lgkmcnt(0)
	v_mfma_f32_16x16x32_bf16 v[72:75], v[96:99], v[56:59], v[72:75]
	s_waitcnt lgkmcnt(0)
	v_mfma_f32_16x16x32_bf16 v[68:71], v[112:115], v[56:59], v[68:71]
	s_nop 7
	v_mul_f32_e32 v45, v64, v64
	v_mov_b32_dpp v32, v64 quad_perm:[1,0,3,2] row_mask:0xf bank_mask:0xf bound_ctrl:1
	v_mov_b32_e32 v44, v64
	v_mov_b32_dpp v33, v45 quad_perm:[1,0,3,2] row_mask:0xf bank_mask:0xf bound_ctrl:1
	v_pk_add_f32 v[32:33], v[44:45], v[32:33]
	s_nop 1
	v_mov_b32_dpp v44, v32 quad_perm:[2,3,0,1] row_mask:0xf bank_mask:0xf bound_ctrl:1
	v_mov_b32_dpp v45, v33 quad_perm:[2,3,0,1] row_mask:0xf bank_mask:0xf bound_ctrl:1
	v_pk_add_f32 v[32:33], v[32:33], v[44:45]
	s_nop 1
	v_mov_b32_dpp v44, v32 row_half_mirror row_mask:0xf bank_mask:0xf bound_ctrl:1
	v_mov_b32_dpp v45, v33 row_half_mirror row_mask:0xf bank_mask:0xf bound_ctrl:1
	v_pk_add_f32 v[32:33], v[32:33], v[44:45]
	s_nop 1
	v_mov_b32_dpp v44, v32 row_mirror row_mask:0xf bank_mask:0xf bound_ctrl:1
	v_mov_b32_dpp v45, v33 row_mirror row_mask:0xf bank_mask:0xf bound_ctrl:1
	s_and_saveexec_b64 s[34:35], s[40:41]
	v_pk_add_f32 v[32:33], v[32:33], v[44:45]
	ds_write_b64 v116, v[32:33]
	s_or_b64 exec, exec, s[34:35]
	v_mul_f32_e32 v45, v65, v65
	v_mov_b32_dpp v32, v65 quad_perm:[1,0,3,2] row_mask:0xf bank_mask:0xf bound_ctrl:1
	v_mov_b32_e32 v44, v65
	v_mov_b32_dpp v33, v45 quad_perm:[1,0,3,2] row_mask:0xf bank_mask:0xf bound_ctrl:1
	v_pk_add_f32 v[32:33], v[44:45], v[32:33]
	s_nop 1
	v_mov_b32_dpp v44, v32 quad_perm:[2,3,0,1] row_mask:0xf bank_mask:0xf bound_ctrl:1
	v_mov_b32_dpp v45, v33 quad_perm:[2,3,0,1] row_mask:0xf bank_mask:0xf bound_ctrl:1
	v_pk_add_f32 v[32:33], v[32:33], v[44:45]
	s_nop 1
	v_mov_b32_dpp v44, v32 row_half_mirror row_mask:0xf bank_mask:0xf bound_ctrl:1
	v_mov_b32_dpp v45, v33 row_half_mirror row_mask:0xf bank_mask:0xf bound_ctrl:1
	v_pk_add_f32 v[32:33], v[32:33], v[44:45]
	s_nop 1
	v_mov_b32_dpp v44, v32 row_mirror row_mask:0xf bank_mask:0xf bound_ctrl:1
	v_mov_b32_dpp v45, v33 row_mirror row_mask:0xf bank_mask:0xf bound_ctrl:1
; #define LAS __attribute__((address_space(3)))
; __device__ __forceinline__ float allred16(float x) { x += dpp_f<0xB1>(x); x += dpp_f<0x4E>(x); x += dpp_f<0x141>(x); x += dpp_f<0x140>(x); return x; }
; __device__ __forceinline__ void ck_consume(const LAS unsigned char* slot, f32x4 (&sacc)[4], LAS unsigned char* st  , int lane, int cw, f32x4& yout, u32x2& vout, f32x4& dout) {
;     ...
;         for (int mt = 0; mt < 2; ++mt) xacc[mt] = __builtin_amdgcn_mfma_f32_16x16x32_bf16(ck_frag(qlo[ks][mt].x, qlo[ks][mt].y, qhi[ks][mt].x, qhi[ks][mt].y), Bs, xacc[mt], 0, 0, 0);
;     }
;     f32x4 Z = __builtin_amdgcn_mfma_f32_16x16x32_bf16(ck_frag(0u, 0u, mk.x, mk.y), ck_frag(0u, 0u, vq.x, vq.y), xacc[0], 0, 0, 0);
; #pragma unroll
;     for (int j = 0; j < 4; ++j) Z = __builtin_amdgcn_mfma_f32_16x16x32_bf16(ck_frag(mn[j].x, mn[j].y, 0u, 0u), ck_frag(pkc(Z[0], Z[1]), pkc(Z[2], Z[3]), vq.x, vq.y), Z, 0, 0, 0);
;     const pg8::bf16x8 UV = ck_frag(pkc(Z[0], Z[1]), pkc(Z[2], Z[3]), vq.x, vq.y);
;     { const f32x4 y = __builtin_amdgcn_mfma_f32_16x16x32_bf16(ck_frag(ylo.x, ylo.y, yhi.x, yhi.y), UV, xacc[1], 0, 0, 0);
;       yout = y; vout = vq; dout = *(const LAS f32x4*)(slot + CK_DOT + 16 * g);
; #pragma unroll
;       for (int r = 0; r < 4; ++r) { const float s1 = allred16(y[r]), s2 = allred16(y[r] * y[r]); if (n == 0) *(LAS f2*)(st + ((4 * g + r) * 4 + cw) * 8) = (f2){s1, s2}; } }
; #pragma unroll
;     for (int kb = 0; kb < 4; ++kb) sacc[kb] = __builtin_amdgcn_mfma_f32_16x16x32_bf16(ck_frag(blo[kb].x, blo[kb].y, bhi[kb].x, bhi[kb].y), UV, sacc[kb], 0, 0, 0) * gm[kb];
; __device__ __forceinline__ void scan_chunked_phase(LAS unsigned char* lds, unsigned char* wsb, const float* kkw, const float* kaw,
;                                                    const float* w0, const float* a0, const float* rk, const float* lng, const float* lnb, int G, int bid, int mode) {
;     ...
;                 for (int cc = 0; cc < 4; ++cc) {
;                     ck_consume(lds + ((rd & 1) * 4 + cc) * CK_SLOT, sacc, lds + CK_ST + (((rd & 1) * 4 + cc) * 16) * 32, lane, wave, py[cc], pvq[cc], pdot[cc]);
; #pragma unroll
;                     for (int r = 0; r < 4; ++r) pgt[cc][r] = Gt[(size_t)b * SEQ * DM + (size_t)(rd * 64 + cc * 16 + 4 * g + r) * DM + col];
	s_and_saveexec_b64 s[34:35], s[40:41]
	v_pk_add_f32 v[32:33], v[32:33], v[44:45]
	ds_write_b64 v116, v[32:33] offset:32
	s_or_b64 exec, exec, s[34:35]
	v_mul_f32_e32 v45, v66, v66
	v_mov_b32_dpp v32, v66 quad_perm:[1,0,3,2] row_mask:0xf bank_mask:0xf bound_ctrl:1
	v_mov_b32_e32 v44, v66
	v_mov_b32_dpp v33, v45 quad_perm:[1,0,3,2] row_mask:0xf bank_mask:0xf bound_ctrl:1
	v_pk_add_f32 v[32:33], v[44:45], v[32:33]
	s_nop 1
	v_mov_b32_dpp v44, v32 quad_perm:[2,3,0,1] row_mask:0xf bank_mask:0xf bound_ctrl:1
	v_mov_b32_dpp v45, v33 quad_perm:[2,3,0,1] row_mask:0xf bank_mask:0xf bound_ctrl:1
	v_pk_add_f32 v[32:33], v[32:33], v[44:45]
	s_nop 1
	v_mov_b32_dpp v44, v32 row_half_mirror row_mask:0xf bank_mask:0xf bound_ctrl:1
	v_mov_b32_dpp v45, v33 row_half_mirror row_mask:0xf bank_mask:0xf bound_ctrl:1
	v_pk_add_f32 v[32:33], v[32:33], v[44:45]
	s_nop 1
	v_mov_b32_dpp v44, v32 row_mirror row_mask:0xf bank_mask:0xf bound_ctrl:1
	v_mov_b32_dpp v45, v33 row_mirror row_mask:0xf bank_mask:0xf bound_ctrl:1
	s_and_saveexec_b64 s[34:35], s[40:41]
	v_pk_add_f32 v[32:33], v[32:33], v[44:45]
	ds_write_b64 v116, v[32:33] offset:64
	s_or_b64 exec, exec, s[34:35]
	v_mul_f32_e32 v45, v67, v67
	v_mov_b32_dpp v32, v67 quad_perm:[1,0,3,2] row_mask:0xf bank_mask:0xf bound_ctrl:1
	v_mov_b32_e32 v44, v67
	v_mov_b32_dpp v33, v45 quad_perm:[1,0,3,2] row_mask:0xf bank_mask:0xf bound_ctrl:1
	v_pk_add_f32 v[32:33], v[44:45], v[32:33]
	s_nop 1
	v_mov_b32_dpp v44, v32 quad_perm:[2,3,0,1] row_mask:0xf bank_mask:0xf bound_ctrl:1
	v_mov_b32_dpp v45, v33 quad_perm:[2,3,0,1] row_mask:0xf bank_mask:0xf bound_ctrl:1
	v_pk_add_f32 v[32:33], v[32:33], v[44:45]
	s_nop 1
	v_mov_b32_dpp v44, v32 row_half_mirror row_mask:0xf bank_mask:0xf bound_ctrl:1
	v_mov_b32_dpp v45, v33 row_half_mirror row_mask:0xf bank_mask:0xf bound_ctrl:1
	v_pk_add_f32 v[32:33], v[32:33], v[44:45]
	s_nop 1
	v_mov_b32_dpp v44, v32 row_mirror row_mask:0xf bank_mask:0xf bound_ctrl:1
	v_mov_b32_dpp v45, v33 row_mirror row_mask:0xf bank_mask:0xf bound_ctrl:1
	s_and_saveexec_b64 s[34:35], s[40:41]
	v_pk_add_f32 v[32:33], v[32:33], v[44:45]
	ds_write_b64 v116, v[32:33] offset:96
	s_or_b64 exec, exec, s[34:35]
	v_add_co_u32_e32 v32, vcc, 0x20000, v158
	v_addc_co_u32_e32 v33, vcc, 0, v159, vcc
	v_add_co_u32_e32 v44, vcc, 0x21000, v158
	s_nop 0
	v_addc_co_u32_e32 v45, vcc, 0, v159, vcc
	v_add_co_u32_e32 v92, vcc, 0x22000, v158
	v_addc_co_u32_e32 v93, vcc, 0, v159, vcc
	v_add_co_u32_e32 v94, vcc, 0x23000, v158
	v_addc_co_u32_e32 v95, vcc, 0, v159, vcc
	global_load_ushort v56, v[32:33], off
	global_load_ushort v57, v[44:45], off
	global_load_ushort v240, v[92:93], off
	global_load_ushort v241, v[94:95], off
	s_or_b32 s2, s2, 3
	s_lshl_b32 s7, s2, 14
	s_add_i32 s7, s7, 0
	v_add_u32_e32 v32, s7, v166
	v_add_u32_e32 v33, v32, v167
	v_pk_mul_f32 v[94:95], v[90:91], v[82:83]
	v_pk_mul_f32 v[92:93], v[88:89], v[80:81]
	v_pk_mul_f32 v[90:91], v[86:87], v[78:79]
	v_pk_mul_f32 v[88:89], v[84:85], v[76:77]
	s_waitcnt lgkmcnt(2)
	v_pk_mul_f32 v[86:87], v[110:111], v[74:75]
	v_pk_mul_f32 v[84:85], v[108:109], v[72:73]
	ds_read2_b64 v[72:75], v33 offset1:4
	v_add_u32_e32 v44, 0x800, v33
	ds_read2_b64 v[76:79], v44 offset0:16 offset1:20
	ds_read2_b64 v[116:119], v33 offset0:8 offset1:12
	ds_read2_b64 v[120:123], v44 offset0:24 offset1:28
	v_add_u32_e32 v44, v32, v169
	v_add_u32_e32 v45, 0x2800, v44
	ds_read2_b64 v[124:127], v45 offset0:160 offset1:240
	v_cvt_pk_bf16_f32 v250, v92, v93
	v_cvt_pk_bf16_f32 v251, v94, v95
	v_cvt_pk_bf16_f32 v252, v88, v89
	v_cvt_pk_bf16_f32 v253, v90, v91
	s_waitcnt lgkmcnt(6)
	v_pk_mul_f32 v[82:83], v[106:107], v[70:71]
	v_pk_mul_f32 v[80:81], v[104:105], v[68:69]
	s_waitcnt lgkmcnt(4)
	v_mfma_f32_16x16x32_bf16 v[72:75], v[72:75], v[250:253], 0
	v_add_u32_e32 v45, 0x3000, v44
	v_add_u32_e32 v33, v32, v168
	ds_read2_b64 v[214:217], v45 offset0:64 offset1:144
	ds_read_b64 v[70:71], v33 offset:8960
	ds_read_b64 v[242:243], v44 offset:14080
	s_waitcnt lgkmcnt(6)
	v_mfma_f32_16x16x32_bf16 v[76:79], v[76:79], v[250:253], 0
	v_cvt_pk_bf16_f32 v250, v84, v85
	v_cvt_pk_bf16_f32 v251, v86, v87
	v_cvt_pk_bf16_f32 v252, v80, v81
	v_cvt_pk_bf16_f32 v253, v82, v83
	v_mov_b32_e32 v68, v129
	v_mov_b32_e32 v69, v129
	s_waitcnt lgkmcnt(5)
	v_mfma_f32_16x16x32_bf16 v[72:75], v[116:119], v[250:253], v[72:75]
	v_mov_b32_e32 v116, v129
	v_mov_b32_e32 v117, v129
	s_waitcnt lgkmcnt(3)
	v_mov_b32_e32 v118, v124
	v_mov_b32_e32 v119, v125
	v_mfma_f32_16x16x32_bf16 v[76:79], v[120:123], v[250:253], v[76:79]
	s_waitcnt lgkmcnt(2)
	v_mov_b32_e32 v120, v214
	v_mov_b32_e32 v121, v215
	v_mov_b32_e32 v122, v129
	s_waitcnt lgkmcnt(1)
	v_mfma_f32_16x16x32_bf16 v[72:75], v[116:119], v[68:71], v[72:75]
	v_mov_b32_e32 v116, v126
	v_mov_b32_e32 v117, v127
	v_mov_b32_e32 v118, v129
	v_mov_b32_e32 v119, v129
	v_mov_b32_e32 v123, v129
	s_nop 2
	v_cvt_pk_bf16_f32 v68, v72, v73
	v_cvt_pk_bf16_f32 v69, v74, v75
	v_add3_u32 v33, s7, v170, v166
	v_add_u32_e32 v33, 0x3800, v33
	v_mfma_f32_16x16x32_bf16 v[72:75], v[116:119], v[68:71], v[72:75]
	v_mov_b32_e32 v116, v216
	v_mov_b32_e32 v117, v217
	v_mov_b32_e32 v244, v129
	v_mov_b32_e32 v245, v129
	ds_read2_b64 v[246:249], v33 offset0:48 offset1:52
	s_nop 2
	v_cvt_pk_bf16_f32 v68, v72, v73
	v_cvt_pk_bf16_f32 v69, v74, v75
	v_add_u32_e32 v44, v32, v170
	v_add_u32_e32 v45, 0x1000, v44
	v_mfma_f32_16x16x32_bf16 v[72:75], v[120:123], v[68:71], v[72:75]
	v_add_u32_e32 v32, v32, v172
	v_add_u32_e32 v33, s7, v171
	ds_read2_b64 v[112:115], v45 offset0:32 offset1:36
	ds_read2_b64 v[104:107], v45 offset0:176 offset1:180
	v_add_u32_e32 v44, 0x1800, v44
	s_nop 2
	v_cvt_pk_bf16_f32 v68, v72, v73
	v_cvt_pk_bf16_f32 v69, v74, v75
	v_add_u32_e32 v32, 0x1000, v32
	ds_read_b128 v[100:103], v33 offset:15872
	ds_read_b128 v[96:99], v33 offset:15936
	v_mfma_f32_16x16x32_bf16 v[72:75], v[116:119], v[68:71], v[72:75]
	ds_read2_b64 v[108:111], v44 offset0:64 offset1:68
	ds_read2_b64 v[124:127], v32 offset0:32 offset1:36
	ds_read_b128 v[120:123], v33 offset:16000
	ds_read_b128 v[116:119], v33 offset:16064
	s_lshl_b32 s2, s2, 9
	s_nop 2
	v_cvt_pk_bf16_f32 v68, v72, v73
	v_cvt_pk_bf16_f32 v69, v74, v75
	s_add_i32 s2, s2, 0
	s_add_i32 s2, s2, 0x24800
	s_waitcnt lgkmcnt(9)
; #define LAS __attribute__((address_space(3)))
; __device__ __forceinline__ float allred16(float x) { x += dpp_f<0xB1>(x); x += dpp_f<0x4E>(x); x += dpp_f<0x141>(x); x += dpp_f<0x140>(x); return x; }
; __device__ __forceinline__ unsigned pkc(float lo, float hi) { f2 v = {lo, hi}; return __builtin_bit_cast(unsigned, __builtin_convertvector(v, bf16x2_t)); }
; __device__ __forceinline__ void ck_consume(const LAS unsigned char* slot, f32x4 (&sacc)[4], LAS unsigned char* st  , int lane, int cw, f32x4& yout, u32x2& vout, f32x4& dout) {
;     ...
;         for (int mt = 0; mt < 2; ++mt) xacc[mt] = __builtin_amdgcn_mfma_f32_16x16x32_bf16(ck_frag(qlo[ks][mt].x, qlo[ks][mt].y, qhi[ks][mt].x, qhi[ks][mt].y), Bs, xacc[mt], 0, 0, 0);
;     }
;     f32x4 Z = __builtin_amdgcn_mfma_f32_16x16x32_bf16(ck_frag(0u, 0u, mk.x, mk.y), ck_frag(0u, 0u, vq.x, vq.y), xacc[0], 0, 0, 0);
; #pragma unroll
;     for (int j = 0; j < 4; ++j) Z = __builtin_amdgcn_mfma_f32_16x16x32_bf16(ck_frag(mn[j].x, mn[j].y, 0u, 0u), ck_frag(pkc(Z[0], Z[1]), pkc(Z[2], Z[3]), vq.x, vq.y), Z, 0, 0, 0);
;     const pg8::bf16x8 UV = ck_frag(pkc(Z[0], Z[1]), pkc(Z[2], Z[3]), vq.x, vq.y);
;     { const f32x4 y = __builtin_amdgcn_mfma_f32_16x16x32_bf16(ck_frag(ylo.x, ylo.y, yhi.x, yhi.y), UV, xacc[1], 0, 0, 0);
;       yout = y; vout = vq; dout = *(const LAS f32x4*)(slot + CK_DOT + 16 * g);
; #pragma unroll
;       for (int r = 0; r < 4; ++r) { const float s1 = allred16(y[r]), s2 = allred16(y[r] * y[r]); if (n == 0) *(LAS f2*)(st + ((4 * g + r) * 4 + cw) * 8) = (f2){s1, s2}; } }
; #pragma unroll
;     for (int kb = 0; kb < 4; ++kb) sacc[kb] = __builtin_amdgcn_mfma_f32_16x16x32_bf16(ck_frag(blo[kb].x, blo[kb].y, bhi[kb].x, bhi[kb].y), UV, sacc[kb], 0, 0, 0) * gm[kb];
; __device__ __forceinline__ void scan_chunked_phase(LAS unsigned char* lds, unsigned char* wsb, const float* kkw, const float* kaw,
;                                                    const float* w0, const float* a0, const float* rk, const float* lng, const float* lnb, int G, int bid, int mode) {
;     ...
;                     for (int r = 0; r < 4; ++r) pgt[cc][r] = Gt[(size_t)b * SEQ * DM + (size_t)(rd * 64 + cc * 16 + 4 * g + r) * DM + col];
;                 }
;                 __syncthreads();
	v_mfma_f32_16x16x32_bf16 v[72:75], v[242:245], v[68:71], v[72:75]
	v_add_u32_e32 v139, s2, v173
	s_nop 6
	v_cvt_pk_bf16_f32 v68, v72, v73
	v_cvt_pk_bf16_f32 v69, v74, v75
	ds_read_b128 v[72:75], v33 offset:16128
	s_waitcnt lgkmcnt(9)
	v_mfma_f32_16x16x32_bf16 v[76:79], v[246:249], v[68:71], v[76:79]
	s_waitcnt lgkmcnt(3)
	v_mfma_f32_16x16x32_bf16 v[88:91], v[104:107], v[68:71], v[88:91]
	s_waitcnt lgkmcnt(0)
	v_mfma_f32_16x16x32_bf16 v[84:87], v[108:111], v[68:71], v[84:87]
	v_mfma_f32_16x16x32_bf16 v[92:95], v[112:115], v[68:71], v[92:95]
	s_waitcnt lgkmcnt(0)
	v_mfma_f32_16x16x32_bf16 v[80:83], v[124:127], v[68:71], v[80:83]
	s_nop 7
	v_mul_f32_e32 v45, v76, v76
	v_mov_b32_dpp v32, v76 quad_perm:[1,0,3,2] row_mask:0xf bank_mask:0xf bound_ctrl:1
	v_mov_b32_e32 v44, v76
	v_mov_b32_dpp v33, v45 quad_perm:[1,0,3,2] row_mask:0xf bank_mask:0xf bound_ctrl:1
	v_pk_add_f32 v[32:33], v[44:45], v[32:33]
	s_nop 1
	v_mov_b32_dpp v44, v32 quad_perm:[2,3,0,1] row_mask:0xf bank_mask:0xf bound_ctrl:1
	v_mov_b32_dpp v45, v33 quad_perm:[2,3,0,1] row_mask:0xf bank_mask:0xf bound_ctrl:1
	v_pk_add_f32 v[32:33], v[32:33], v[44:45]
	s_nop 1
	v_mov_b32_dpp v44, v32 row_half_mirror row_mask:0xf bank_mask:0xf bound_ctrl:1
	v_mov_b32_dpp v45, v33 row_half_mirror row_mask:0xf bank_mask:0xf bound_ctrl:1
	v_pk_add_f32 v[32:33], v[32:33], v[44:45]
	s_nop 1
	v_mov_b32_dpp v44, v32 row_mirror row_mask:0xf bank_mask:0xf bound_ctrl:1
	v_mov_b32_dpp v45, v33 row_mirror row_mask:0xf bank_mask:0xf bound_ctrl:1
	s_and_saveexec_b64 s[34:35], s[40:41]
	v_pk_add_f32 v[32:33], v[32:33], v[44:45]
	ds_write_b64 v139, v[32:33]
	s_or_b64 exec, exec, s[34:35]
	v_mul_f32_e32 v45, v77, v77
	v_mov_b32_dpp v32, v77 quad_perm:[1,0,3,2] row_mask:0xf bank_mask:0xf bound_ctrl:1
	v_mov_b32_e32 v44, v77
	v_mov_b32_dpp v33, v45 quad_perm:[1,0,3,2] row_mask:0xf bank_mask:0xf bound_ctrl:1
	v_pk_add_f32 v[32:33], v[44:45], v[32:33]
	s_nop 1
	v_mov_b32_dpp v44, v32 quad_perm:[2,3,0,1] row_mask:0xf bank_mask:0xf bound_ctrl:1
	v_mov_b32_dpp v45, v33 quad_perm:[2,3,0,1] row_mask:0xf bank_mask:0xf bound_ctrl:1
	v_pk_add_f32 v[32:33], v[32:33], v[44:45]
	s_nop 1
	v_mov_b32_dpp v44, v32 row_half_mirror row_mask:0xf bank_mask:0xf bound_ctrl:1
	v_mov_b32_dpp v45, v33 row_half_mirror row_mask:0xf bank_mask:0xf bound_ctrl:1
	v_pk_add_f32 v[32:33], v[32:33], v[44:45]
	s_nop 1
	v_mov_b32_dpp v44, v32 row_mirror row_mask:0xf bank_mask:0xf bound_ctrl:1
	v_mov_b32_dpp v45, v33 row_mirror row_mask:0xf bank_mask:0xf bound_ctrl:1
	s_and_saveexec_b64 s[34:35], s[40:41]
	v_pk_add_f32 v[32:33], v[32:33], v[44:45]
	ds_write_b64 v139, v[32:33] offset:32
	s_or_b64 exec, exec, s[34:35]
	v_mul_f32_e32 v45, v78, v78
	v_mov_b32_dpp v32, v78 quad_perm:[1,0,3,2] row_mask:0xf bank_mask:0xf bound_ctrl:1
	v_mov_b32_e32 v44, v78
	v_mov_b32_dpp v33, v45 quad_perm:[1,0,3,2] row_mask:0xf bank_mask:0xf bound_ctrl:1
	v_pk_add_f32 v[32:33], v[44:45], v[32:33]
	s_nop 1
	v_mov_b32_dpp v44, v32 quad_perm:[2,3,0,1] row_mask:0xf bank_mask:0xf bound_ctrl:1
	v_mov_b32_dpp v45, v33 quad_perm:[2,3,0,1] row_mask:0xf bank_mask:0xf bound_ctrl:1
	v_pk_add_f32 v[32:33], v[32:33], v[44:45]
	s_nop 1
	v_mov_b32_dpp v44, v32 row_half_mirror row_mask:0xf bank_mask:0xf bound_ctrl:1
	v_mov_b32_dpp v45, v33 row_half_mirror row_mask:0xf bank_mask:0xf bound_ctrl:1
	v_pk_add_f32 v[32:33], v[32:33], v[44:45]
	s_nop 1
	v_mov_b32_dpp v44, v32 row_mirror row_mask:0xf bank_mask:0xf bound_ctrl:1
	v_mov_b32_dpp v45, v33 row_mirror row_mask:0xf bank_mask:0xf bound_ctrl:1
	s_and_saveexec_b64 s[34:35], s[40:41]
	v_pk_add_f32 v[32:33], v[32:33], v[44:45]
	ds_write_b64 v139, v[32:33] offset:64
	s_or_b64 exec, exec, s[34:35]
	v_mul_f32_e32 v45, v79, v79
	v_mov_b32_dpp v32, v79 quad_perm:[1,0,3,2] row_mask:0xf bank_mask:0xf bound_ctrl:1
	v_mov_b32_e32 v44, v79
	v_mov_b32_dpp v33, v45 quad_perm:[1,0,3,2] row_mask:0xf bank_mask:0xf bound_ctrl:1
	v_pk_add_f32 v[32:33], v[44:45], v[32:33]
	s_nop 1
	v_mov_b32_dpp v44, v32 quad_perm:[2,3,0,1] row_mask:0xf bank_mask:0xf bound_ctrl:1
	v_mov_b32_dpp v45, v33 quad_perm:[2,3,0,1] row_mask:0xf bank_mask:0xf bound_ctrl:1
	v_pk_add_f32 v[32:33], v[32:33], v[44:45]
	s_nop 1
	v_mov_b32_dpp v44, v32 row_half_mirror row_mask:0xf bank_mask:0xf bound_ctrl:1
	v_mov_b32_dpp v45, v33 row_half_mirror row_mask:0xf bank_mask:0xf bound_ctrl:1
	v_pk_add_f32 v[32:33], v[32:33], v[44:45]
	s_nop 1
	v_mov_b32_dpp v44, v32 row_mirror row_mask:0xf bank_mask:0xf bound_ctrl:1
	v_mov_b32_dpp v45, v33 row_mirror row_mask:0xf bank_mask:0xf bound_ctrl:1
	s_and_saveexec_b64 s[34:35], s[40:41]
	v_pk_add_f32 v[32:33], v[32:33], v[44:45]
	ds_write_b64 v139, v[32:33] offset:96
	s_or_b64 exec, exec, s[34:35]
	v_add_co_u32_e32 v32, vcc, 0x30000, v158
	v_addc_co_u32_e32 v33, vcc, 0, v159, vcc
	v_add_co_u32_e32 v104, vcc, 0x31000, v158
	v_addc_co_u32_e32 v105, vcc, 0, v159, vcc
	v_add_co_u32_e32 v106, vcc, 0x32000, v158
	s_nop 0
	v_addc_co_u32_e32 v107, vcc, 0, v159, vcc
	v_add_co_u32_e32 v108, vcc, 0x33000, v158
	v_addc_co_u32_e32 v109, vcc, 0, v159, vcc
	global_load_ushort v44, v[32:33], off
	global_load_ushort v45, v[104:105], off
	s_nop 0
	global_load_ushort v104, v[106:107], off
	global_load_ushort v105, v[108:109], off
	v_pk_mul_f32 v[94:95], v[102:103], v[94:95]
	v_pk_mul_f32 v[92:93], v[100:101], v[92:93]
	v_pk_mul_f32 v[90:91], v[98:99], v[90:91]
	v_pk_mul_f32 v[88:89], v[96:97], v[88:89]
	s_waitcnt lgkmcnt(2)
	v_pk_mul_f32 v[86:87], v[122:123], v[86:87]
	v_pk_mul_f32 v[84:85], v[120:121], v[84:85]
	s_waitcnt lgkmcnt(1)
	v_pk_mul_f32 v[82:83], v[118:119], v[82:83]
	v_pk_mul_f32 v[80:81], v[116:117], v[80:81]
	s_waitcnt lgkmcnt(0)
	s_barrier
	s_add_i32 s10, s10, 64
	s_addk_i32 s27, 0x800
	s_add_i32 s28, s28, -1
	v_add_u32_e32 v128, 0x20000, v128
	s_add_i32 s29, s29, 4
	s_branch .LBB0_116
